# convert_p (mixer_pre phase tail): loads of the first seven loop trips issued at phase start into registers the mixer items never touch, converted and stored after the items; original loop runs the rem
# speedup vs baseline: 1.0042x; 1.0042x over previous
; __device__ __forceinline__ unsigned pk2(float lo, float hi) { return pg8::cvt_pk_bf16(lo, hi); }
; __device__ __forceinline__ void convert_p(const float* p, bf16_t* pbf, size_t gtid, size_t gthreads) {
;     asm volatile("" : "+v"(gtid));
;     const size_t n8 = (size_t)T * PLE / 8;
;     for (size_t i = gtid; i < n8; i += gthreads) { const f32x4 a = ((const f32x4*)p)[2 * i], b = ((const f32x4*)p)[2 * i + 1];
;         u32x4v w; w.x = pk2(a[0], a[1]); w.y = pk2(a[2], a[3]); w.z = pk2(b[0], b[1]); w.w = pk2(b[2], b[3]); ((u32x4v*)pbf)[i] = w; }
; __global__ void __launch_bounds__(NTHR, 2) hymba_fwd(Args args) {
;     ...
;         for (int it = vcu; it < NBATCH * 64; it += G) mixer_pre_item(it, in, l, ws, lds, tid, lane, wave);
;         { int t_ = threadIdx.x; asm volatile("" : "+v"(t_)); convert_p(in[1] + (size_t)l * T * PLE, PBF, (size_t)bid * NTHR + t_, (size_t)G * NTHR); }
.LBB0_564:
	s_or_b64 exec, exec, s[10:11]
	v_readlane_b32 s0, v251, 61
	v_readlane_b32 s1, v251, 62
	s_mov_b32 s91, s83
	s_andn2_b64 vcc, exec, s[0:1]
	s_waitcnt lgkmcnt(0)
	s_barrier
	v_readlane_b32 s100, v249, 5
	v_readlane_b32 s101, v249, 6
	v_mov_b32_e32 v106, v158
	v_ashrrev_i32_e32 v107, 31, v106
	s_nop 0
	v_lshl_add_u64 v[106:107], s[100:101], 0, v[106:107]
	v_lshlrev_b64 v[106:107], 5, v[106:107]
	v_readlane_b32 s100, v248, 2
	v_readlane_b32 s101, v248, 3
	s_nop 1
	v_lshl_add_u64 v[106:107], s[100:101], 0, v[106:107]
	s_lshl_b64 s[100:101], s[90:91], 25
	v_lshl_add_u64 v[106:107], s[100:101], 0, v[106:107]
	global_load_dwordx4 v[78:81], v[106:107], off offset:-16
	global_load_dwordx4 v[82:85], v[106:107], off
	v_lshl_add_u64 v[106:107], v[106:107], 0, s[16:17]
	global_load_dwordx4 v[86:89], v[106:107], off offset:-16
	global_load_dwordx4 v[90:93], v[106:107], off
	v_lshl_add_u64 v[106:107], v[106:107], 0, s[16:17]
	global_load_dwordx4 v[94:97], v[106:107], off offset:-16
	global_load_dwordx4 v[98:101], v[106:107], off
	v_lshl_add_u64 v[106:107], v[106:107], 0, s[16:17]
	global_load_dwordx4 v[102:105], v[106:107], off offset:-16
	global_load_dwordx4 v[184:187], v[106:107], off
	v_lshl_add_u64 v[106:107], v[106:107], 0, s[16:17]
	global_load_dwordx4 v[188:191], v[106:107], off offset:-16
	global_load_dwordx4 v[192:195], v[106:107], off
	v_lshl_add_u64 v[106:107], v[106:107], 0, s[16:17]
	global_load_dwordx4 v[196:199], v[106:107], off offset:-16
	global_load_dwordx4 v[200:203], v[106:107], off
	v_lshl_add_u64 v[106:107], v[106:107], 0, s[16:17]
	global_load_dwordx4 v[204:207], v[106:107], off offset:-16
	global_load_dwordx4 v[238:241], v[106:107], off
	s_cbranch_vccnz .LBB0_743
	s_mul_i32 s82, s90, 0xc00
	v_readlane_b32 s48, v248, 55
	s_lshl_b64 s[0:1], s[82:83], 2
	v_readlane_b32 s56, v248, 63
	v_readlane_b32 s57, v250, 0
	s_add_u32 s10, s56, s0
	s_addc_u32 s11, s57, s1
	s_lshl_b32 s0, s90, 2
	s_lshl_b64 s[6:7], s[90:91], 12
	v_readlane_b32 s12, v249, 62
	v_readlane_b32 s13, v249, 63
	s_add_u32 s12, s12, s6
	s_addc_u32 s13, s13, s7
	s_lshl_b32 s1, s90, 8
	s_add_u32 s6, s66, s97
	s_addc_u32 s7, s67, 0
	v_readlane_b32 s14, v248, 0
	v_readlane_b32 s15, v248, 1
	s_add_u32 s6, s6, 0x2b80000
	v_readlane_b32 s82, v250, 19
	s_addc_u32 s7, s7, 0
	v_readlane_b32 s8, v249, 61
	v_readlane_b32 s14, v248, 16
	v_readlane_b32 s49, v248, 56
	v_readlane_b32 s50, v248, 57
	v_readlane_b32 s51, v248, 58
	v_readlane_b32 s52, v248, 59
	v_readlane_b32 s53, v248, 60
	v_readlane_b32 s54, v248, 61
	v_readlane_b32 s55, v248, 62
	v_readlane_b32 s58, v250, 1
	v_readlane_b32 s59, v250, 2
	v_readlane_b32 s60, v250, 3
	v_readlane_b32 s61, v250, 4
	v_readlane_b32 s62, v250, 5
	v_readlane_b32 s63, v250, 6
	v_readlane_b32 s15, v248, 17
	s_branch .LBB0_567

; __device__ __forceinline__ unsigned pk2(float lo, float hi) { return pg8::cvt_pk_bf16(lo, hi); }
; __device__ __forceinline__ void convert_p(const float* p, bf16_t* pbf, size_t gtid, size_t gthreads) {
;     asm volatile("" : "+v"(gtid));
;     const size_t n8 = (size_t)T * PLE / 8;
;     for (size_t i = gtid; i < n8; i += gthreads) { const f32x4 a = ((const f32x4*)p)[2 * i], b = ((const f32x4*)p)[2 * i + 1];
;         u32x4v w; w.x = pk2(a[0], a[1]); w.y = pk2(a[2], a[3]); w.z = pk2(b[0], b[1]); w.w = pk2(b[2], b[3]); ((u32x4v*)pbf)[i] = w; }
.LBB0_743:
	v_mov_b32_e32 v2, v158
	v_readlane_b32 s0, v249, 5
	v_readlane_b32 s1, v249, 6
	v_ashrrev_i32_e32 v3, 31, v2
	s_nop 0
	v_lshl_add_u64 v[2:3], s[0:1], 0, v[2:3]
	s_mov_b64 s[0:1], 0x100000
	s_nop 0
	v_cmp_gt_u64_e32 vcc, s[0:1], v[2:3]
	s_and_saveexec_b64 s[10:11], vcc
	v_readlane_b32 s8, v249, 7
	v_readlane_b32 s9, v249, 8
	s_cbranch_execz .LBB0_746
	v_readlane_b32 s6, v251, 6
	v_readlane_b32 s7, v251, 7
	s_lshl_b64 s[0:1], s[90:91], 25
	v_lshlrev_b64 v[6:7], 5, v[2:3]
	v_lshl_add_u64 v[4:5], v[2:3], 4, s[6:7]
	v_readlane_b32 s6, v248, 2
	s_add_u32 s0, s6, s0
	v_readlane_b32 s6, v248, 3
	s_addc_u32 s1, s6, s1
	v_lshl_add_u64 v[6:7], s[0:1], 0, v[6:7]
	s_mov_b64 s[12:13], 0
	s_waitcnt vmcnt(0)
	v_cvt_pk_bf16_f32 v8, v78, v79
	v_cvt_pk_bf16_f32 v9, v80, v81
	v_cvt_pk_bf16_f32 v10, v82, v83
	v_cvt_pk_bf16_f32 v11, v84, v85
	global_store_dwordx4 v[4:5], v[8:11], off
	v_lshl_add_u64 v[4:5], v[4:5], 0, s[92:93]
	v_lshl_add_u64 v[2:3], v[2:3], 0, s[8:9]
	v_lshl_add_u64 v[6:7], v[6:7], 0, s[16:17]
	v_cvt_pk_bf16_f32 v12, v86, v87
	v_cvt_pk_bf16_f32 v13, v88, v89
	v_cvt_pk_bf16_f32 v14, v90, v91
	v_cvt_pk_bf16_f32 v15, v92, v93
	global_store_dwordx4 v[4:5], v[12:15], off
	v_lshl_add_u64 v[4:5], v[4:5], 0, s[92:93]
	v_lshl_add_u64 v[2:3], v[2:3], 0, s[8:9]
	v_lshl_add_u64 v[6:7], v[6:7], 0, s[16:17]
	v_cvt_pk_bf16_f32 v8, v94, v95
	v_cvt_pk_bf16_f32 v9, v96, v97
	v_cvt_pk_bf16_f32 v10, v98, v99
	v_cvt_pk_bf16_f32 v11, v100, v101
	global_store_dwordx4 v[4:5], v[8:11], off
	v_lshl_add_u64 v[4:5], v[4:5], 0, s[92:93]
	v_lshl_add_u64 v[2:3], v[2:3], 0, s[8:9]
	v_lshl_add_u64 v[6:7], v[6:7], 0, s[16:17]
	v_cvt_pk_bf16_f32 v12, v102, v103
	v_cvt_pk_bf16_f32 v13, v104, v105
	v_cvt_pk_bf16_f32 v14, v184, v185
	v_cvt_pk_bf16_f32 v15, v186, v187
	global_store_dwordx4 v[4:5], v[12:15], off
	v_lshl_add_u64 v[4:5], v[4:5], 0, s[92:93]
	v_lshl_add_u64 v[2:3], v[2:3], 0, s[8:9]
	v_lshl_add_u64 v[6:7], v[6:7], 0, s[16:17]
	v_cvt_pk_bf16_f32 v8, v188, v189
	v_cvt_pk_bf16_f32 v9, v190, v191
	v_cvt_pk_bf16_f32 v10, v192, v193
	v_cvt_pk_bf16_f32 v11, v194, v195
	global_store_dwordx4 v[4:5], v[8:11], off
	v_lshl_add_u64 v[4:5], v[4:5], 0, s[92:93]
	v_lshl_add_u64 v[2:3], v[2:3], 0, s[8:9]
	v_lshl_add_u64 v[6:7], v[6:7], 0, s[16:17]
	v_cvt_pk_bf16_f32 v12, v196, v197
	v_cvt_pk_bf16_f32 v13, v198, v199
	v_cvt_pk_bf16_f32 v14, v200, v201
	v_cvt_pk_bf16_f32 v15, v202, v203
	global_store_dwordx4 v[4:5], v[12:15], off
	v_lshl_add_u64 v[4:5], v[4:5], 0, s[92:93]
	v_lshl_add_u64 v[2:3], v[2:3], 0, s[8:9]
	v_lshl_add_u64 v[6:7], v[6:7], 0, s[16:17]
	v_cvt_pk_bf16_f32 v8, v204, v205
	v_cvt_pk_bf16_f32 v9, v206, v207
	v_cvt_pk_bf16_f32 v10, v238, v239
	v_cvt_pk_bf16_f32 v11, v240, v241
	global_store_dwordx4 v[4:5], v[8:11], off
	v_lshl_add_u64 v[4:5], v[4:5], 0, s[92:93]
	v_lshl_add_u64 v[2:3], v[2:3], 0, s[8:9]
	v_lshl_add_u64 v[6:7], v[6:7], 0, s[16:17]
	s_nop 1
